# adds NA masked-tile rpb lookups batched (16 LDS reads, one wait, fmac+cndmask) and packed fma in diff-attn exp block; split patch without flag register
# speedup vs baseline: 1.0345x; 1.0071x over previous
.LBB0_399:
	s_or_b64 exec, exec, s[30:31]
	s_waitcnt lgkmcnt(4)
	ds_read_b64_tr_b16 v[102:103], v181 offset:16384
	ds_read_b64_tr_b16 v[98:99], v181 offset:16416
	ds_read_b64_tr_b16 v[104:105], v181 offset:20992
	ds_read_b64_tr_b16 v[100:101], v181 offset:21024
	s_waitcnt lgkmcnt(4)
	ds_read_b64_tr_b16 v[110:111], v180 offset:16384
	ds_read_b64_tr_b16 v[106:107], v180 offset:16416
	ds_read_b64_tr_b16 v[112:113], v180 offset:20992
	ds_read_b64_tr_b16 v[108:109], v180 offset:21024
	s_mov_b64 s[30:31], -1
	s_and_b64 vcc, exec, s[66:67]
	s_cbranch_vccz .LBB0_433
	ds_read_b32 v116, v221
	ds_read_b32 v114, v221 offset:4
	ds_read_b32 v118, v221 offset:8
	ds_read_b32 v117, v221 offset:12
	ds_read_b32 v120, v221 offset:64
	ds_read_b32 v119, v221 offset:68
	ds_read_b32 v122, v221 offset:72
	ds_read_b32 v121, v221 offset:76
	ds_read_b32 v124, v221 offset:128
	ds_read_b32 v123, v221 offset:132
	ds_read_b32 v126, v221 offset:136
	ds_read_b32 v125, v221 offset:140
	ds_read_b32 v128, v221 offset:192
	ds_read_b32 v127, v221 offset:196
	ds_read_b32 v130, v221 offset:200
	ds_read_b32 v129, v221 offset:204
	v_mov_b32_e32 v131, 0xff800000
	s_waitcnt lgkmcnt(0)
	v_fmac_f32_e32 v116, 0x3e0293ee, v0
	v_fmac_f32_e32 v114, 0x3e0293ee, v1
	v_fmac_f32_e32 v118, 0x3e0293ee, v2
	v_fmac_f32_e32 v117, 0x3e0293ee, v3
	v_fmac_f32_e32 v120, 0x3e0293ee, v4
	v_fmac_f32_e32 v119, 0x3e0293ee, v5
	v_fmac_f32_e32 v122, 0x3e0293ee, v6
	v_fmac_f32_e32 v121, 0x3e0293ee, v7
	v_fmac_f32_e32 v124, 0x3e0293ee, v12
	v_fmac_f32_e32 v123, 0x3e0293ee, v13
	v_fmac_f32_e32 v126, 0x3e0293ee, v14
	v_fmac_f32_e32 v125, 0x3e0293ee, v15
	v_fmac_f32_e32 v128, 0x3e0293ee, v8
	v_fmac_f32_e32 v127, 0x3e0293ee, v9
	v_fmac_f32_e32 v130, 0x3e0293ee, v10
	v_fmac_f32_e32 v129, 0x3e0293ee, v11
	v_cndmask_b32_e64 v116, v131, v116, s[14:15]
	v_cndmask_b32_e64 v114, v131, v114, s[16:17]
	v_cndmask_b32_e64 v118, v131, v118, s[18:19]
	v_cndmask_b32_e64 v117, v131, v117, s[20:21]
	v_cndmask_b32_e64 v120, v131, v120, s[52:53]
	v_cndmask_b32_e64 v119, v131, v119, s[94:95]
	v_cndmask_b32_e64 v122, v131, v122, s[76:77]
	v_cndmask_b32_e64 v121, v131, v121, s[60:61]
	v_cndmask_b32_e64 v124, v131, v124, s[62:63]
	v_cndmask_b32_e64 v123, v131, v123, s[68:69]
	v_cndmask_b32_e64 v126, v131, v126, s[92:93]
	v_cndmask_b32_e64 v125, v131, v125, s[96:97]
	v_cndmask_b32_e64 v128, v131, v128, s[22:23]
	v_cndmask_b32_e64 v127, v131, v127, s[24:25]
	v_cndmask_b32_e64 v130, v131, v130, s[26:27]
	v_cndmask_b32_e64 v129, v131, v129, s[28:29]
.LBB0_432:
	v_max3_f32 v115, v116, s64, v114
	v_max3_f32 v115, v115, v118, v117
	v_max3_f32 v115, v115, v120, v119
	v_max3_f32 v115, v115, v122, v121
	v_max3_f32 v115, v115, v124, v123
	v_max3_f32 v115, v115, v126, v125
	v_max3_f32 v115, v115, v128, v127
	v_max3_f32 v115, v115, v130, v129
	s_mov_b64 s[30:31], 0

.LBB0_459:
	v_pk_fma_f32 v[142:143], v[142:143], s[42:43], v[216:217] op_sel:[0,0,1] op_sel_hi:[1,0,1] neg_lo:[0,0,1] neg_hi:[0,0,1]
	v_pk_fma_f32 v[144:145], v[144:145], s[42:43], v[216:217] op_sel:[0,0,1] op_sel_hi:[1,0,1] neg_lo:[0,0,1] neg_hi:[0,0,1]
	v_pk_fma_f32 v[134:135], v[134:135], s[42:43], v[216:217] op_sel:[0,0,1] op_sel_hi:[1,0,1] neg_lo:[0,0,1] neg_hi:[0,0,1]
	v_pk_fma_f32 v[136:137], v[136:137], s[42:43], v[216:217] op_sel:[0,0,1] op_sel_hi:[1,0,1] neg_lo:[0,0,1] neg_hi:[0,0,1]
	v_pk_fma_f32 v[126:127], v[126:127], s[42:43], v[216:217] op_sel:[0,0,1] op_sel_hi:[1,0,1] neg_lo:[0,0,1] neg_hi:[0,0,1]
	v_pk_fma_f32 v[128:129], v[128:129], s[42:43], v[216:217] op_sel:[0,0,1] op_sel_hi:[1,0,1] neg_lo:[0,0,1] neg_hi:[0,0,1]
	v_pk_fma_f32 v[118:119], v[118:119], s[42:43], v[216:217] op_sel:[0,0,1] op_sel_hi:[1,0,1] neg_lo:[0,0,1] neg_hi:[0,0,1]
	v_pk_fma_f32 v[120:121], v[120:121], s[42:43], v[216:217] op_sel:[0,0,1] op_sel_hi:[1,0,1] neg_lo:[0,0,1] neg_hi:[0,0,1]
	v_pk_fma_f32 v[138:139], v[138:139], s[42:43], v[218:219] op_sel_hi:[1,0,0] neg_lo:[0,0,1] neg_hi:[0,0,1]
	v_pk_fma_f32 v[140:141], v[140:141], s[42:43], v[218:219] op_sel_hi:[1,0,0] neg_lo:[0,0,1] neg_hi:[0,0,1]
	v_pk_fma_f32 v[130:131], v[130:131], s[42:43], v[218:219] op_sel_hi:[1,0,0] neg_lo:[0,0,1] neg_hi:[0,0,1]
	v_pk_fma_f32 v[132:133], v[132:133], s[42:43], v[218:219] op_sel_hi:[1,0,0] neg_lo:[0,0,1] neg_hi:[0,0,1]
	v_pk_fma_f32 v[122:123], v[122:123], s[42:43], v[218:219] op_sel_hi:[1,0,0] neg_lo:[0,0,1] neg_hi:[0,0,1]
	v_pk_fma_f32 v[124:125], v[124:125], s[42:43], v[218:219] op_sel_hi:[1,0,0] neg_lo:[0,0,1] neg_hi:[0,0,1]
	v_pk_fma_f32 v[114:115], v[114:115], s[42:43], v[218:219] op_sel_hi:[1,0,0] neg_lo:[0,0,1] neg_hi:[0,0,1]
	v_pk_fma_f32 v[116:117], v[116:117], s[42:43], v[218:219] op_sel_hi:[1,0,0] neg_lo:[0,0,1] neg_hi:[0,0,1]
	v_exp_f32_e32 v142, v142
	v_exp_f32_e32 v143, v143
	v_exp_f32_e32 v144, v144
	v_exp_f32_e32 v145, v145
	v_exp_f32_e32 v134, v134
	v_exp_f32_e32 v135, v135
	v_exp_f32_e32 v136, v136
	v_exp_f32_e32 v137, v137
	v_exp_f32_e32 v126, v126
	v_exp_f32_e32 v127, v127
	v_exp_f32_e32 v128, v128
	v_exp_f32_e32 v129, v129
	v_exp_f32_e32 v118, v118
	v_exp_f32_e32 v119, v119
	v_exp_f32_e32 v120, v120
	v_exp_f32_e32 v121, v121
	v_exp_f32_e32 v138, v138
	v_exp_f32_e32 v139, v139
	v_exp_f32_e32 v140, v140
	v_exp_f32_e32 v141, v141
	v_exp_f32_e32 v130, v130
	v_exp_f32_e32 v131, v131
	v_exp_f32_e32 v132, v132
	v_exp_f32_e32 v133, v133
	v_exp_f32_e32 v122, v122
	v_exp_f32_e32 v123, v123
	v_exp_f32_e32 v124, v124
	v_exp_f32_e32 v125, v125
	v_exp_f32_e32 v114, v114
	v_exp_f32_e32 v115, v115
	v_exp_f32_e32 v116, v116
	v_exp_f32_e32 v117, v117
	v_cvt_pk_bf16_f32 v196, v142, v143
	v_cvt_pk_bf16_f32 v197, v144, v145
	v_cvt_pk_bf16_f32 v198, v134, v135
	v_cvt_pk_bf16_f32 v199, v136, v137
	v_cvt_pk_bf16_f32 v200, v126, v127
	v_cvt_pk_bf16_f32 v201, v128, v129
	v_cvt_pk_bf16_f32 v202, v118, v119
	v_cvt_pk_bf16_f32 v203, v120, v121
	v_cvt_pk_bf16_f32 v204, v138, v139
	v_cvt_pk_bf16_f32 v205, v140, v141
	v_cvt_pk_bf16_f32 v206, v130, v131
	v_cvt_pk_bf16_f32 v207, v132, v133
	v_cvt_pk_bf16_f32 v208, v122, v123
	v_cvt_pk_bf16_f32 v209, v124, v125
	v_cvt_pk_bf16_f32 v210, v114, v115
	v_cvt_pk_bf16_f32 v211, v116, v117
	ds_read_b64_tr_b16 v[222:223], v17 offset:21056
	ds_read_b64_tr_b16 v[220:221], v17 offset:16448
	ds_read_b64_tr_b16 v[226:227], v17 offset:21088
	ds_read_b64_tr_b16 v[224:225], v17 offset:16480
	ds_read_b64_tr_b16 v[228:229], v17 offset:25664
	ds_read_b64_tr_b16 v[230:231], v17 offset:30272
	ds_read_b64_tr_b16 v[234:235], v17 offset:30304
	ds_read_b64_tr_b16 v[232:233], v17 offset:25696
	s_waitcnt lgkmcnt(8)
	v_mfma_f32_16x16x32_bf16 v[70:73], v[102:105], v[196:199], v[70:73]
	v_mfma_f32_16x16x32_bf16 v[78:81], v[102:105], v[204:207], v[78:81]
	v_mfma_f32_16x16x32_bf16 v[66:69], v[98:101], v[196:199], v[66:69]
	v_mfma_f32_16x16x32_bf16 v[74:77], v[98:101], v[204:207], v[74:77]
	v_mfma_f32_16x16x32_bf16 v[70:73], v[106:109], v[200:203], v[70:73]
	v_mfma_f32_16x16x32_bf16 v[78:81], v[106:109], v[208:211], v[78:81]
	v_mfma_f32_16x16x32_bf16 v[66:69], v[110:113], v[200:203], v[66:69]
	v_mfma_f32_16x16x32_bf16 v[74:77], v[110:113], v[208:211], v[74:77]
	ds_read_b64_tr_b16 v[100:101], v17 offset:21120
	ds_read_b64_tr_b16 v[98:99], v17 offset:16512
	ds_read_b64_tr_b16 v[104:105], v17 offset:21152
	ds_read_b64_tr_b16 v[102:103], v17 offset:16544
	ds_read_b64_tr_b16 v[106:107], v17 offset:25728
	ds_read_b64_tr_b16 v[108:109], v17 offset:30336
	ds_read_b64_tr_b16 v[112:113], v17 offset:30368
	ds_read_b64_tr_b16 v[110:111], v17 offset:25760
	s_waitcnt lgkmcnt(14)
	v_mfma_f32_16x16x32_bf16 v[54:57], v[220:223], v[196:199], v[54:57]
	v_mfma_f32_16x16x32_bf16 v[62:65], v[220:223], v[204:207], v[62:65]
	s_waitcnt lgkmcnt(12)
	v_mfma_f32_16x16x32_bf16 v[50:53], v[224:227], v[196:199], v[50:53]
	v_mfma_f32_16x16x32_bf16 v[58:61], v[224:227], v[204:207], v[58:61]
	s_waitcnt lgkmcnt(10)
	v_mfma_f32_16x16x32_bf16 v[54:57], v[228:231], v[200:203], v[54:57]
	v_mfma_f32_16x16x32_bf16 v[62:65], v[228:231], v[208:211], v[62:65]
	s_waitcnt lgkmcnt(8)
	v_mfma_f32_16x16x32_bf16 v[50:53], v[232:235], v[200:203], v[50:53]
	v_mfma_f32_16x16x32_bf16 v[58:61], v[232:235], v[208:211], v[58:61]
	ds_read_b64_tr_b16 v[222:223], v17 offset:21184
	ds_read_b64_tr_b16 v[220:221], v17 offset:16576
	ds_read_b64_tr_b16 v[226:227], v17 offset:21216
	ds_read_b64_tr_b16 v[224:225], v17 offset:16608
	ds_read_b64_tr_b16 v[228:229], v17 offset:25792
	ds_read_b64_tr_b16 v[230:231], v17 offset:30400
	ds_read_b64_tr_b16 v[234:235], v17 offset:30432
	ds_read_b64_tr_b16 v[232:233], v17 offset:25824
	s_waitcnt lgkmcnt(14)
	v_mfma_f32_16x16x32_bf16 v[38:41], v[98:101], v[196:199], v[38:41]
	s_add_i32 s31, s30, 1
	s_cmp_ge_u32 s31, s29
	v_mfma_f32_16x16x32_bf16 v[46:49], v[98:101], v[204:207], v[46:49]
	s_waitcnt lgkmcnt(12)
	v_mfma_f32_16x16x32_bf16 v[34:37], v[102:105], v[196:199], v[34:37]
	v_mfma_f32_16x16x32_bf16 v[42:45], v[102:105], v[204:207], v[42:45]
	s_waitcnt lgkmcnt(6)
	v_mfma_f32_16x16x32_bf16 v[26:29], v[220:223], v[196:199], v[26:29]
	v_mfma_f32_16x16x32_bf16 v[30:33], v[220:223], v[204:207], v[30:33]
	s_waitcnt lgkmcnt(4)
	v_mfma_f32_16x16x32_bf16 v[22:25], v[224:227], v[196:199], v[22:25]
	v_mfma_f32_16x16x32_bf16 v[12:15], v[224:227], v[204:207], v[12:15]
	v_mfma_f32_16x16x32_bf16 v[38:41], v[106:109], v[200:203], v[38:41]
	v_mfma_f32_16x16x32_bf16 v[46:49], v[106:109], v[208:211], v[46:49]
	v_mfma_f32_16x16x32_bf16 v[34:37], v[110:113], v[200:203], v[34:37]
	v_mfma_f32_16x16x32_bf16 v[42:45], v[110:113], v[208:211], v[42:45]
	s_waitcnt lgkmcnt(2)
	v_mfma_f32_16x16x32_bf16 v[26:29], v[228:231], v[200:203], v[26:29]
	v_mfma_f32_16x16x32_bf16 v[30:33], v[228:231], v[208:211], v[30:33]
	s_waitcnt lgkmcnt(0)
	v_mfma_f32_16x16x32_bf16 v[22:25], v[232:235], v[200:203], v[22:25]
	v_mfma_f32_16x16x32_bf16 v[12:15], v[232:235], v[208:211], v[12:15]
	s_cbranch_scc1 .LBB0_461
	s_bitcmp1_b32 s31, 0
	s_cselect_b32 s48, 0x8800, 0
	s_add_i32 s48, s48, 0
	v_add3_u32 v17, s48, v147, v163
	v_add3_u32 v98, s48, v164, v165
	v_add3_u32 v99, s48, v170, v171
	v_add3_u32 v100, s48, v172, v171
	s_waitcnt vmcnt(3)
	ds_write_b128 v17, v[82:85]
	s_waitcnt vmcnt(2)
	ds_write_b128 v98, v[86:89]
	s_waitcnt vmcnt(1)
	ds_write_b128 v99, v[90:93] offset:16384
	s_waitcnt vmcnt(0)
	ds_write_b128 v100, v[94:97] offset:16384

.Lpeer_extra:
	s_setprio 0
	s_lshl_b32 s62, s49, 14
	s_sub_i32 s63, s52, s80
	s_lshl_b32 s63, s63, 4
	s_mov_b32 s61, 4
	s_mov_b32 s101, 15
	s_mov_b64 s[34:35], 0
	v_add_u32_e32 v223, 8, v215
	s_branch .LBB0_732

.LBB0_802:
	s_cmp_lt_u32 s90, 4
	s_cbranch_scc1 .Lpeer_normal_exit
	s_cmp_eq_u64 s[26:27], 0
	s_cbranch_scc0 .Lpeer_normal_exit
	s_mov_b64 exec, -1
	s_branch .LBB0_727
